# c41: merge epilogue row groups 6-7 issue their sixteen gate / partial-sum loads together instead of one load and wait per fragment
# speedup vs baseline: 1.0001x; 1.0001x over previous
; __device__ __forceinline__ unsigned pk2(float lo, float hi) { f32x2 v = {lo, hi}; bf16x2_t b = __builtin_convertvector(v, bf16x2_t); return __builtin_bit_cast(unsigned, b); }
; __device__ __forceinline__ float bflo(unsigned u) { return __uint_as_float(u << 16); }
; __device__ __forceinline__ float bfhi(unsigned u) { return __uint_as_float(u & 0xffff0000u); }
; __device__ __forceinline__ void st4bf(bf16_t* dst, f32x4 v) { u32x2 pk; pk.x = pk2(v.x, v.y); pk.y = pk2(v.z, v.w); *(u32x2*)dst = pk; }
; __device__ void merge_phase(const Params& p, int l, unsigned char* smem) {
;     ...
;             for (int mi = 0; mi < 8; ++mi) {
;                 const int row = m0 + wm * 128 + mi * 16 + idx;
;                 const float rs = (br == 2) ? rstd[row] : 1.f;
; #pragma unroll
;                 for (int ni = 0; ni < 4; ++ni) {
;                     const int col = n0 + wn * 64 + ni * 16 + 4 * kq;
;                     const u32x2 g = *(const u32x2*)(MG + (size_t)row * 3072 + br * 1024 + col);
;                     f32x4 gv; gv.x = bflo(g.x); gv.y = bfhi(g.x); gv.z = bflo(g.y); gv.w = bfhi(g.y);
;                     f32x4 v = gv * rs * acc[mi][ni];
;                     bf16_t* mp = MR + (size_t)row * 1024 + col;
;                     if (mi < 6) {
;                         if (br > 0) { const u32x2 o = mpk[mi < 6 ? mi : 0][ni]; v.x += bflo(o.x); v.y += bfhi(o.x); v.z += bflo(o.y); v.w += bfhi(o.y); }
;                         u32x2 pk; pk.x = pk2(v.x, v.y); pk.y = pk2(v.z, v.w); mpk[mi < 6 ? mi : 0][ni] = pk;
;                         if (br == 2) *(u32x2*)mp = pk;
;                     } else {
;                         if (br > 0) { const u32x2 o = *(const u32x2*)mp; v.x += bflo(o.x); v.y += bfhi(o.x); v.z += bflo(o.y); v.w += bfhi(o.y); }
;                         st4bf(mp, v);
;                     }
.LBB0_1210:
	v_or_b32_e32 v247, 0x60, v180
	v_mad_u32_u24 v206, v247, s5, v80
	v_add_u32_e32 v207, 0x18000, v206
	v_lshl_add_u32 v208, v247, 11, v80
	v_add_u32_e32 v209, 0x8000, v208
	v_mov_b32_e32 v248, 1.0
	v_mov_b32_e32 v250, 1.0
	s_cmp_eq_u32 s90, 2
	s_cbranch_scc0 .Lmg_nors
	v_lshlrev_b32_e32 v246, 2, v247
	global_load_dword v248, v246, s[42:43]
	global_load_dword v250, v246, s[42:43] offset:64
.Lmg_nors:
	global_load_dwordx2 v[190:191], v206, s[60:61]
	global_load_dwordx2 v[192:193], v206, s[60:61] offset:32
	global_load_dwordx2 v[194:195], v206, s[60:61] offset:64
	global_load_dwordx2 v[196:197], v206, s[60:61] offset:96
	global_load_dwordx2 v[198:199], v207, s[60:61]
	global_load_dwordx2 v[200:201], v207, s[60:61] offset:32
	global_load_dwordx2 v[202:203], v207, s[60:61] offset:64
	global_load_dwordx2 v[204:205], v207, s[60:61] offset:96
	s_cmp_eq_u32 s90, 0
	s_cbranch_scc1 .Lmg_first
	global_load_dwordx2 v[230:231], v208, s[44:45]
	global_load_dwordx2 v[232:233], v208, s[44:45] offset:32
	global_load_dwordx2 v[234:235], v208, s[44:45] offset:64
	global_load_dwordx2 v[236:237], v208, s[44:45] offset:96
	global_load_dwordx2 v[238:239], v209, s[44:45]
	global_load_dwordx2 v[240:241], v209, s[44:45] offset:32
	global_load_dwordx2 v[242:243], v209, s[44:45] offset:64
	global_load_dwordx2 v[244:245], v209, s[44:45] offset:96
	s_waitcnt vmcnt(0)
	v_lshlrev_b32_e32 v186, 16, v190
	v_and_b32_e32 v187, 0xffff0000, v190
	v_lshlrev_b32_e32 v188, 16, v191
	v_and_b32_e32 v189, 0xffff0000, v191
	v_pk_mul_f32 v[186:187], v[248:249], v[186:187] op_sel_hi:[0,1]
	v_pk_mul_f32 v[188:189], v[248:249], v[188:189] op_sel_hi:[0,1]
	v_pk_mul_f32 v[28:29], v[28:29], v[186:187]
	v_pk_mul_f32 v[30:31], v[30:31], v[188:189]
	v_lshlrev_b32_e32 v186, 16, v230
	v_and_b32_e32 v187, 0xffff0000, v230
	v_lshlrev_b32_e32 v188, 16, v231
	v_and_b32_e32 v189, 0xffff0000, v231
	v_pk_add_f32 v[28:29], v[28:29], v[186:187]
	v_pk_add_f32 v[30:31], v[30:31], v[188:189]
	v_cvt_pk_bf16_f32 v28, v28, v29
	v_cvt_pk_bf16_f32 v29, v30, v31
	global_store_dwordx2 v208, v[28:29], s[44:45]
	v_lshlrev_b32_e32 v186, 16, v192
	v_and_b32_e32 v187, 0xffff0000, v192
	v_lshlrev_b32_e32 v188, 16, v193
	v_and_b32_e32 v189, 0xffff0000, v193
	v_pk_mul_f32 v[186:187], v[248:249], v[186:187] op_sel_hi:[0,1]
	v_pk_mul_f32 v[188:189], v[248:249], v[188:189] op_sel_hi:[0,1]
	v_pk_mul_f32 v[24:25], v[24:25], v[186:187]
	v_pk_mul_f32 v[26:27], v[26:27], v[188:189]
	v_lshlrev_b32_e32 v186, 16, v232
	v_and_b32_e32 v187, 0xffff0000, v232
	v_lshlrev_b32_e32 v188, 16, v233
	v_and_b32_e32 v189, 0xffff0000, v233
	v_pk_add_f32 v[24:25], v[24:25], v[186:187]
	v_pk_add_f32 v[26:27], v[26:27], v[188:189]
	v_cvt_pk_bf16_f32 v24, v24, v25
	v_cvt_pk_bf16_f32 v25, v26, v27
	global_store_dwordx2 v208, v[24:25], s[44:45] offset:32
	v_lshlrev_b32_e32 v186, 16, v194
	v_and_b32_e32 v187, 0xffff0000, v194
	v_lshlrev_b32_e32 v188, 16, v195
	v_and_b32_e32 v189, 0xffff0000, v195
	v_pk_mul_f32 v[186:187], v[248:249], v[186:187] op_sel_hi:[0,1]
	v_pk_mul_f32 v[188:189], v[248:249], v[188:189] op_sel_hi:[0,1]
	v_pk_mul_f32 v[20:21], v[20:21], v[186:187]
	v_pk_mul_f32 v[22:23], v[22:23], v[188:189]
	v_lshlrev_b32_e32 v186, 16, v234
	v_and_b32_e32 v187, 0xffff0000, v234
	v_lshlrev_b32_e32 v188, 16, v235
	v_and_b32_e32 v189, 0xffff0000, v235
	v_pk_add_f32 v[20:21], v[20:21], v[186:187]
	v_pk_add_f32 v[22:23], v[22:23], v[188:189]
	v_cvt_pk_bf16_f32 v20, v20, v21
	v_cvt_pk_bf16_f32 v21, v22, v23
	global_store_dwordx2 v208, v[20:21], s[44:45] offset:64
	v_lshlrev_b32_e32 v186, 16, v196
	v_and_b32_e32 v187, 0xffff0000, v196
	v_lshlrev_b32_e32 v188, 16, v197
	v_and_b32_e32 v189, 0xffff0000, v197
	v_pk_mul_f32 v[186:187], v[248:249], v[186:187] op_sel_hi:[0,1]
	v_pk_mul_f32 v[188:189], v[248:249], v[188:189] op_sel_hi:[0,1]
	v_pk_mul_f32 v[16:17], v[16:17], v[186:187]
	v_pk_mul_f32 v[18:19], v[18:19], v[188:189]
	v_lshlrev_b32_e32 v186, 16, v236
	v_and_b32_e32 v187, 0xffff0000, v236
	v_lshlrev_b32_e32 v188, 16, v237
	v_and_b32_e32 v189, 0xffff0000, v237
	v_pk_add_f32 v[16:17], v[16:17], v[186:187]
	v_pk_add_f32 v[18:19], v[18:19], v[188:189]
	v_cvt_pk_bf16_f32 v16, v16, v17
	v_cvt_pk_bf16_f32 v17, v18, v19
	global_store_dwordx2 v208, v[16:17], s[44:45] offset:96
	v_lshlrev_b32_e32 v186, 16, v198
	v_and_b32_e32 v187, 0xffff0000, v198
	v_lshlrev_b32_e32 v188, 16, v199
	v_and_b32_e32 v189, 0xffff0000, v199
	v_pk_mul_f32 v[186:187], v[250:251], v[186:187] op_sel_hi:[0,1]
	v_pk_mul_f32 v[188:189], v[250:251], v[188:189] op_sel_hi:[0,1]
	v_pk_mul_f32 v[12:13], v[12:13], v[186:187]
	v_pk_mul_f32 v[14:15], v[14:15], v[188:189]
	v_lshlrev_b32_e32 v186, 16, v238
	v_and_b32_e32 v187, 0xffff0000, v238
	v_lshlrev_b32_e32 v188, 16, v239
	v_and_b32_e32 v189, 0xffff0000, v239
	v_pk_add_f32 v[12:13], v[12:13], v[186:187]
	v_pk_add_f32 v[14:15], v[14:15], v[188:189]
	v_cvt_pk_bf16_f32 v12, v12, v13
	v_cvt_pk_bf16_f32 v13, v14, v15
	global_store_dwordx2 v209, v[12:13], s[44:45]
	v_lshlrev_b32_e32 v186, 16, v200
	v_and_b32_e32 v187, 0xffff0000, v200
	v_lshlrev_b32_e32 v188, 16, v201
	v_and_b32_e32 v189, 0xffff0000, v201
	v_pk_mul_f32 v[186:187], v[250:251], v[186:187] op_sel_hi:[0,1]
	v_pk_mul_f32 v[188:189], v[250:251], v[188:189] op_sel_hi:[0,1]
	v_pk_mul_f32 v[8:9], v[8:9], v[186:187]
	v_pk_mul_f32 v[10:11], v[10:11], v[188:189]
	v_lshlrev_b32_e32 v186, 16, v240
	v_and_b32_e32 v187, 0xffff0000, v240
	v_lshlrev_b32_e32 v188, 16, v241
	v_and_b32_e32 v189, 0xffff0000, v241
	v_pk_add_f32 v[8:9], v[8:9], v[186:187]
	v_pk_add_f32 v[10:11], v[10:11], v[188:189]
	v_cvt_pk_bf16_f32 v8, v8, v9
	v_cvt_pk_bf16_f32 v9, v10, v11
	global_store_dwordx2 v209, v[8:9], s[44:45] offset:32
	v_lshlrev_b32_e32 v186, 16, v202
	v_and_b32_e32 v187, 0xffff0000, v202
	v_lshlrev_b32_e32 v188, 16, v203
	v_and_b32_e32 v189, 0xffff0000, v203
	v_pk_mul_f32 v[186:187], v[250:251], v[186:187] op_sel_hi:[0,1]
	v_pk_mul_f32 v[188:189], v[250:251], v[188:189] op_sel_hi:[0,1]
	v_pk_mul_f32 v[4:5], v[4:5], v[186:187]
	v_pk_mul_f32 v[6:7], v[6:7], v[188:189]
	v_lshlrev_b32_e32 v186, 16, v242
	v_and_b32_e32 v187, 0xffff0000, v242
	v_lshlrev_b32_e32 v188, 16, v243
	v_and_b32_e32 v189, 0xffff0000, v243
	v_pk_add_f32 v[4:5], v[4:5], v[186:187]
	v_pk_add_f32 v[6:7], v[6:7], v[188:189]
	v_cvt_pk_bf16_f32 v4, v4, v5
	v_cvt_pk_bf16_f32 v5, v6, v7
	global_store_dwordx2 v209, v[4:5], s[44:45] offset:64
	v_lshlrev_b32_e32 v186, 16, v204
	v_and_b32_e32 v187, 0xffff0000, v204
	v_lshlrev_b32_e32 v188, 16, v205
	v_and_b32_e32 v189, 0xffff0000, v205
	v_pk_mul_f32 v[186:187], v[250:251], v[186:187] op_sel_hi:[0,1]
	v_pk_mul_f32 v[188:189], v[250:251], v[188:189] op_sel_hi:[0,1]
	v_pk_mul_f32 v[0:1], v[0:1], v[186:187]
	v_pk_mul_f32 v[2:3], v[2:3], v[188:189]
	v_lshlrev_b32_e32 v186, 16, v244
	v_and_b32_e32 v187, 0xffff0000, v244
	v_lshlrev_b32_e32 v188, 16, v245
	v_and_b32_e32 v189, 0xffff0000, v245
	v_pk_add_f32 v[0:1], v[0:1], v[186:187]
	v_pk_add_f32 v[2:3], v[2:3], v[188:189]
	s_branch .Lmg_done
; __device__ __forceinline__ unsigned pk2(float lo, float hi) { f32x2 v = {lo, hi}; bf16x2_t b = __builtin_convertvector(v, bf16x2_t); return __builtin_bit_cast(unsigned, b); }
; __device__ __forceinline__ float bflo(unsigned u) { return __uint_as_float(u << 16); }
; __device__ __forceinline__ float bfhi(unsigned u) { return __uint_as_float(u & 0xffff0000u); }
; __device__ __forceinline__ void st4bf(bf16_t* dst, f32x4 v) { u32x2 pk; pk.x = pk2(v.x, v.y); pk.y = pk2(v.z, v.w); *(u32x2*)dst = pk; }
; __device__ void merge_phase(const Params& p, int l, unsigned char* smem) {
;     ...
;             for (int mi = 0; mi < 8; ++mi) {
;                 const int row = m0 + wm * 128 + mi * 16 + idx;
;                 const float rs = (br == 2) ? rstd[row] : 1.f;
; #pragma unroll
;                 for (int ni = 0; ni < 4; ++ni) {
;                     const int col = n0 + wn * 64 + ni * 16 + 4 * kq;
;                     const u32x2 g = *(const u32x2*)(MG + (size_t)row * 3072 + br * 1024 + col);
;                     f32x4 gv; gv.x = bflo(g.x); gv.y = bfhi(g.x); gv.z = bflo(g.y); gv.w = bfhi(g.y);
;                     f32x4 v = gv * rs * acc[mi][ni];
;                     bf16_t* mp = MR + (size_t)row * 1024 + col;
;                     if (mi < 6) {
;                         if (br > 0) { const u32x2 o = mpk[mi < 6 ? mi : 0][ni]; v.x += bflo(o.x); v.y += bfhi(o.x); v.z += bflo(o.y); v.w += bfhi(o.y); }
;                         u32x2 pk; pk.x = pk2(v.x, v.y); pk.y = pk2(v.z, v.w); mpk[mi < 6 ? mi : 0][ni] = pk;
;                         if (br == 2) *(u32x2*)mp = pk;
;                     } else {
;                         if (br > 0) { const u32x2 o = *(const u32x2*)mp; v.x += bflo(o.x); v.y += bfhi(o.x); v.z += bflo(o.y); v.w += bfhi(o.y); }
;                         st4bf(mp, v);
;                     }
.Lmg_first:
	s_waitcnt vmcnt(0)
	v_lshlrev_b32_e32 v186, 16, v190
	v_and_b32_e32 v187, 0xffff0000, v190
	v_lshlrev_b32_e32 v188, 16, v191
	v_and_b32_e32 v189, 0xffff0000, v191
	v_pk_mul_f32 v[186:187], v[248:249], v[186:187] op_sel_hi:[0,1]
	v_pk_mul_f32 v[188:189], v[248:249], v[188:189] op_sel_hi:[0,1]
	v_pk_mul_f32 v[28:29], v[28:29], v[186:187]
	v_pk_mul_f32 v[30:31], v[30:31], v[188:189]
	v_cvt_pk_bf16_f32 v28, v28, v29
	v_cvt_pk_bf16_f32 v29, v30, v31
	global_store_dwordx2 v208, v[28:29], s[44:45]
	v_lshlrev_b32_e32 v186, 16, v192
	v_and_b32_e32 v187, 0xffff0000, v192
	v_lshlrev_b32_e32 v188, 16, v193
	v_and_b32_e32 v189, 0xffff0000, v193
	v_pk_mul_f32 v[186:187], v[248:249], v[186:187] op_sel_hi:[0,1]
	v_pk_mul_f32 v[188:189], v[248:249], v[188:189] op_sel_hi:[0,1]
	v_pk_mul_f32 v[24:25], v[24:25], v[186:187]
	v_pk_mul_f32 v[26:27], v[26:27], v[188:189]
	v_cvt_pk_bf16_f32 v24, v24, v25
	v_cvt_pk_bf16_f32 v25, v26, v27
	global_store_dwordx2 v208, v[24:25], s[44:45] offset:32
	v_lshlrev_b32_e32 v186, 16, v194
	v_and_b32_e32 v187, 0xffff0000, v194
	v_lshlrev_b32_e32 v188, 16, v195
	v_and_b32_e32 v189, 0xffff0000, v195
	v_pk_mul_f32 v[186:187], v[248:249], v[186:187] op_sel_hi:[0,1]
	v_pk_mul_f32 v[188:189], v[248:249], v[188:189] op_sel_hi:[0,1]
	v_pk_mul_f32 v[20:21], v[20:21], v[186:187]
	v_pk_mul_f32 v[22:23], v[22:23], v[188:189]
	v_cvt_pk_bf16_f32 v20, v20, v21
	v_cvt_pk_bf16_f32 v21, v22, v23
	global_store_dwordx2 v208, v[20:21], s[44:45] offset:64
	v_lshlrev_b32_e32 v186, 16, v196
	v_and_b32_e32 v187, 0xffff0000, v196
	v_lshlrev_b32_e32 v188, 16, v197
	v_and_b32_e32 v189, 0xffff0000, v197
	v_pk_mul_f32 v[186:187], v[248:249], v[186:187] op_sel_hi:[0,1]
	v_pk_mul_f32 v[188:189], v[248:249], v[188:189] op_sel_hi:[0,1]
	v_pk_mul_f32 v[16:17], v[16:17], v[186:187]
	v_pk_mul_f32 v[18:19], v[18:19], v[188:189]
	v_cvt_pk_bf16_f32 v16, v16, v17
	v_cvt_pk_bf16_f32 v17, v18, v19
	global_store_dwordx2 v208, v[16:17], s[44:45] offset:96
	v_lshlrev_b32_e32 v186, 16, v198
	v_and_b32_e32 v187, 0xffff0000, v198
	v_lshlrev_b32_e32 v188, 16, v199
	v_and_b32_e32 v189, 0xffff0000, v199
	v_pk_mul_f32 v[186:187], v[250:251], v[186:187] op_sel_hi:[0,1]
	v_pk_mul_f32 v[188:189], v[250:251], v[188:189] op_sel_hi:[0,1]
	v_pk_mul_f32 v[12:13], v[12:13], v[186:187]
	v_pk_mul_f32 v[14:15], v[14:15], v[188:189]
	v_cvt_pk_bf16_f32 v12, v12, v13
	v_cvt_pk_bf16_f32 v13, v14, v15
	global_store_dwordx2 v209, v[12:13], s[44:45]
	v_lshlrev_b32_e32 v186, 16, v200
	v_and_b32_e32 v187, 0xffff0000, v200
	v_lshlrev_b32_e32 v188, 16, v201
	v_and_b32_e32 v189, 0xffff0000, v201
	v_pk_mul_f32 v[186:187], v[250:251], v[186:187] op_sel_hi:[0,1]
	v_pk_mul_f32 v[188:189], v[250:251], v[188:189] op_sel_hi:[0,1]
	v_pk_mul_f32 v[8:9], v[8:9], v[186:187]
	v_pk_mul_f32 v[10:11], v[10:11], v[188:189]
	v_cvt_pk_bf16_f32 v8, v8, v9
	v_cvt_pk_bf16_f32 v9, v10, v11
	global_store_dwordx2 v209, v[8:9], s[44:45] offset:32
	v_lshlrev_b32_e32 v186, 16, v202
	v_and_b32_e32 v187, 0xffff0000, v202
	v_lshlrev_b32_e32 v188, 16, v203
	v_and_b32_e32 v189, 0xffff0000, v203
	v_pk_mul_f32 v[186:187], v[250:251], v[186:187] op_sel_hi:[0,1]
	v_pk_mul_f32 v[188:189], v[250:251], v[188:189] op_sel_hi:[0,1]
	v_pk_mul_f32 v[4:5], v[4:5], v[186:187]
	v_pk_mul_f32 v[6:7], v[6:7], v[188:189]
	v_cvt_pk_bf16_f32 v4, v4, v5
	v_cvt_pk_bf16_f32 v5, v6, v7
	global_store_dwordx2 v209, v[4:5], s[44:45] offset:64
	v_lshlrev_b32_e32 v186, 16, v204
	v_and_b32_e32 v187, 0xffff0000, v204
	v_lshlrev_b32_e32 v188, 16, v205
	v_and_b32_e32 v189, 0xffff0000, v205
	v_pk_mul_f32 v[186:187], v[250:251], v[186:187] op_sel_hi:[0,1]
	v_pk_mul_f32 v[188:189], v[250:251], v[188:189] op_sel_hi:[0,1]
	v_pk_mul_f32 v[0:1], v[0:1], v[186:187]
	v_pk_mul_f32 v[2:3], v[2:3], v[188:189]
.Lmg_done:
	v_mov_b32_e32 v12, v209
	v_mov_b32_e32 v13, v81
	v_lshl_add_u64 v[12:13], s[44:45], 0, v[12:13]
	s_branch .LBB0_1094
